# v018 + attention: far-tile bias constant kept in a VGPR per unit, single max seed, packed running exp-sum (10 fewer adds per tile)
# baseline (speedup 1.0000x reference)
.LBB0_2757:
	v_mov_b32_e32 v8, v242
	s_lshl_b32 s8, s4, 7
	s_sub_i32 s14, 0x1fff, s8
	v_ashrrev_i32_e32 v9, 4, v8
	v_add_u32_e32 v2, s80, v9
	v_min_i32_e32 v4, s14, v2
	v_readlane_b32 s4, v255, 11
	v_ashrrev_i32_e32 v5, 31, v4
	s_add_i32 s4, s3, s4
	v_and_b32_e32 v10, 15, v8
	v_lshlrev_b64 v[4:5], 12, v[4:5]
	s_ashr_i32 s5, s4, 31
	v_bitop3_b32 v6, v9, v10, 7 bitop3:0x6c
	v_lshl_add_u64 v[4:5], s[78:79], 0, v[4:5]
	s_lshl_b64 s[4:5], s[4:5], 1
	v_lshl_add_u64 v[4:5], v[4:5], 0, s[4:5]
	v_lshlrev_b32_e32 v2, 4, v6
	s_mov_b32 m0, s97
	v_lshl_add_u64 v[4:5], v[4:5], 0, v[2:3]
	global_load_lds_dwordx4 v[4:5], off
	v_add_u32_e32 v4, s82, v9
	v_bitop3_b32 v6, v4, v10, 7 bitop3:0x6c
	v_min_i32_e32 v4, s14, v4
	v_ashrrev_i32_e32 v5, 31, v4
	v_lshlrev_b64 v[4:5], 12, v[4:5]
	v_lshl_add_u64 v[4:5], s[78:79], 0, v[4:5]
	v_lshl_add_u64 v[4:5], v[4:5], 0, s[4:5]
	v_lshlrev_b32_e32 v6, 4, v6
	v_mov_b32_e32 v7, v3
	v_lshl_add_u64 v[4:5], v[4:5], 0, v[6:7]
	s_add_i32 m0, s83, 0
	s_lshl_b32 s44, s3, 1
	global_load_lds_dwordx4 v[4:5], off
	v_add_u32_e32 v4, s86, v9
	v_min_i32_e32 v4, s14, v4
	v_ashrrev_i32_e32 v5, 31, v4
	v_lshlrev_b64 v[4:5], 12, v[4:5]
	v_lshl_add_u64 v[4:5], s[78:79], 0, v[4:5]
	v_lshl_add_u64 v[4:5], v[4:5], 0, s[4:5]
	v_lshl_add_u64 v[4:5], v[4:5], 0, v[2:3]
	s_add_i32 m0, s87, 0
	v_add_u32_e32 v2, s90, v9
	global_load_lds_dwordx4 v[4:5], off
	v_min_i32_e32 v4, s14, v2
	v_ashrrev_i32_e32 v5, 31, v4
	v_lshlrev_b64 v[4:5], 12, v[4:5]
	v_bitop3_b32 v6, v2, v10, 7 bitop3:0x6c
	v_lshl_add_u64 v[4:5], s[78:79], 0, v[4:5]
	v_lshl_add_u64 v[4:5], v[4:5], 0, s[4:5]
	v_lshlrev_b32_e32 v2, 4, v6
	v_lshl_add_u64 v[4:5], v[4:5], 0, v[2:3]
	v_lshrrev_b32_e32 v2, 2, v8
	v_and_or_b32 v2, v2, 7, s96
	v_min_i32_e32 v6, s14, v2
	s_add_i32 m0, s91, 0
	v_ashrrev_i32_e32 v7, 31, v6
	global_load_lds_dwordx4 v[4:5], off
	v_and_b32_e32 v4, 0xffffffe0, v8
	v_lshlrev_b32_e32 v5, 3, v8
	v_lshlrev_b64 v[6:7], 12, v[6:7]
	v_and_or_b32 v4, v5, 24, v4
	v_lshl_add_u64 v[6:7], s[50:51], 0, v[6:7]
	v_lshl_add_u64 v[6:7], v[6:7], 0, s[44:45]
	v_ashrrev_i32_e32 v5, 31, v4
	v_lshl_add_u64 v[4:5], v[4:5], 1, v[6:7]
	s_mov_b32 m0, s42
	v_lshl_add_u64 v[6:7], v[4:5], 0, s[58:59]
	global_load_lds_dwordx4 v[4:5], off
	s_add_i32 m0, s97, 0x10400
	s_sub_i32 s15, 0x2000, s8
	global_load_lds_dwordx4 v[6:7], off
	v_lshl_add_u64 v[6:7], v[4:5], 0, s[52:53]
	s_add_i32 m0, s97, 0x10800
	v_lshl_add_u64 v[4:5], v[4:5], 0, s[48:49]
	global_load_lds_dwordx4 v[6:7], off
	s_add_i32 m0, s97, 0x10c00
	s_ashr_i32 s16, s15, 6
	global_load_lds_dwordx4 v[4:5], off
	s_waitcnt vmcnt(0)
	s_cmp_lt_i32 s16, 1
	s_waitcnt vmcnt(0) lgkmcnt(0)
	s_barrier
	s_cbranch_scc1 .LBB0_2779
	v_lshlrev_b32_e32 v252, 4, v242
	v_lshlrev_b32_e32 v253, 3, v242
	v_and_b32_e32 v252, 0xc0, v252
	v_and_or_b32 v252, v253, 24, v252
	v_and_b32_e32 v253, 0x100, v253
	v_or_b32_e32 v252, v252, v253
	v_lshlrev_b32_e32 v253, 1, v242
	v_and_b32_e32 v253, 32, v253
	v_or_b32_e32 v252, v252, v253
	v_mov_b32_e32 v253, 0x20000
	ds_read_b32 v253, v253
	s_waitcnt lgkmcnt(0)
	s_lshl_b32 s2, s2, 7
	s_add_i32 s2, s2, s46
	s_ashr_i32 s17, s2, 6
	s_add_u32 s2, s78, s4
	s_addc_u32 s3, s79, s5
	v_mov_b32_e32 v16, v3
	v_mov_b32_e32 v17, v3
	s_add_u32 s4, s50, s44
	v_mov_b32_e32 v2, v3
	v_mov_b32_e32 v4, v3
	v_mov_b32_e32 v5, v3
	v_mov_b32_e32 v6, v3
	v_mov_b32_e32 v7, v3
	v_mov_b32_e32 v8, v3
	v_mov_b32_e32 v9, v3
	v_mov_b32_e32 v10, v3
	v_mov_b32_e32 v11, v3
	v_mov_b32_e32 v12, v3
	v_mov_b32_e32 v13, v3
	v_mov_b32_e32 v14, v3
	v_mov_b32_e32 v15, v3
	v_mov_b64_e32 v[128:129], v[16:17]
	v_mov_b64_e32 v[112:113], v[16:17]
	v_mov_b64_e32 v[144:145], v[16:17]
	v_mov_b64_e32 v[96:97], v[16:17]
	v_mov_b64_e32 v[80:81], v[16:17]
	v_mov_b64_e32 v[64:65], v[16:17]
	v_mov_b64_e32 v[48:49], v[16:17]
	v_mov_b64_e32 v[32:33], v[16:17]
	s_addc_u32 s5, s51, 0
	s_add_i32 s18, s47, s8
	s_mov_b32 s19, 0
	v_mov_b32_e32 v251, 0xf149f2ca
	v_mov_b32_e32 v250, 0
	s_mov_b32 s20, 0
	s_mov_b32 s21, 0
	v_mov_b64_e32 v[126:127], v[14:15]
	v_mov_b64_e32 v[124:125], v[12:13]
	v_mov_b64_e32 v[122:123], v[10:11]
	v_mov_b64_e32 v[120:121], v[8:9]
	v_mov_b64_e32 v[118:119], v[6:7]
	v_mov_b64_e32 v[116:117], v[4:5]
	v_mov_b64_e32 v[114:115], v[2:3]
	v_mov_b64_e32 v[110:111], v[14:15]
	v_mov_b64_e32 v[108:109], v[12:13]
	v_mov_b64_e32 v[106:107], v[10:11]
	v_mov_b64_e32 v[104:105], v[8:9]
	v_mov_b64_e32 v[102:103], v[6:7]
	v_mov_b64_e32 v[100:101], v[4:5]
	v_mov_b64_e32 v[98:99], v[2:3]
	v_mov_b64_e32 v[142:143], v[14:15]
	v_mov_b64_e32 v[140:141], v[12:13]
	v_mov_b64_e32 v[138:139], v[10:11]
	v_mov_b64_e32 v[136:137], v[8:9]
	v_mov_b64_e32 v[134:135], v[6:7]
	v_mov_b64_e32 v[132:133], v[4:5]
	v_mov_b64_e32 v[130:131], v[2:3]
	v_mov_b64_e32 v[94:95], v[14:15]
	v_mov_b64_e32 v[92:93], v[12:13]
	v_mov_b64_e32 v[90:91], v[10:11]
	v_mov_b64_e32 v[88:89], v[8:9]
	v_mov_b64_e32 v[86:87], v[6:7]
	v_mov_b64_e32 v[84:85], v[4:5]
	v_mov_b64_e32 v[82:83], v[2:3]
	v_mov_b64_e32 v[78:79], v[14:15]
	v_mov_b64_e32 v[76:77], v[12:13]
	v_mov_b64_e32 v[74:75], v[10:11]
	v_mov_b64_e32 v[72:73], v[8:9]
	v_mov_b64_e32 v[70:71], v[6:7]
	v_mov_b64_e32 v[68:69], v[4:5]
	v_mov_b64_e32 v[66:67], v[2:3]
	v_mov_b64_e32 v[62:63], v[14:15]
	v_mov_b64_e32 v[60:61], v[12:13]
	v_mov_b64_e32 v[58:59], v[10:11]
	v_mov_b64_e32 v[56:57], v[8:9]
	v_mov_b64_e32 v[54:55], v[6:7]
	v_mov_b64_e32 v[52:53], v[4:5]
	v_mov_b64_e32 v[50:51], v[2:3]
	v_mov_b64_e32 v[46:47], v[14:15]
	v_mov_b64_e32 v[44:45], v[12:13]
	v_mov_b64_e32 v[42:43], v[10:11]
	v_mov_b64_e32 v[40:41], v[8:9]
	v_mov_b64_e32 v[38:39], v[6:7]
	v_mov_b64_e32 v[36:37], v[4:5]
	v_mov_b64_e32 v[34:35], v[2:3]
	v_mov_b64_e32 v[30:31], v[14:15]
	v_mov_b64_e32 v[28:29], v[12:13]
	v_mov_b64_e32 v[26:27], v[10:11]
	v_mov_b64_e32 v[24:25], v[8:9]
	v_mov_b64_e32 v[22:23], v[6:7]
	v_mov_b64_e32 v[20:21], v[4:5]
	v_mov_b64_e32 v[18:19], v[2:3]
	s_branch .LBB0_2761

.LBB0_2765:
	s_andn2_b64 vcc, exec, s[8:9]
	s_cbranch_vccnz .LBB0_2775
	s_and_b32 s22, s21, 0x8000
	v_ashrrev_i32_e32 v16, 5, v242
	v_and_b32_e32 v2, 31, v242
	s_add_i32 s8, s43, s22
	v_lshlrev_b32_e32 v17, 4, v16
	v_lshlrev_b32_e32 v190, 4, v242
	v_and_b32_e32 v190, 0x70, v190
	v_lshl_add_u32 v191, v2, 8, s8
	v_add_u32_e32 v12, 32, v17
	v_xad_u32 v8, v17, v190, v191
	v_xad_u32 v178, v12, v190, v191
	ds_read_b128 v[4:7], v8
	ds_read_b128 v[8:11], v8 offset:8192
	ds_read_b128 v[12:15], v178
	ds_read_b128 v[178:181], v178 offset:8192
	v_add_u32_e32 v182, 64, v17
	v_xad_u32 v186, v182, v190, v191
	ds_read_b128 v[182:185], v186
	ds_read_b128 v[186:189], v186 offset:8192
	s_waitcnt lgkmcnt(0)
	v_mfma_f32_32x32x16_bf16 v[162:177], v[4:7], v[210:213], 0
	v_mfma_f32_32x32x16_bf16 v[146:161], v[8:11], v[210:213], 0
	v_add_u32_e32 v4, 0x60, v17
	v_xad_u32 v8, v4, v190, v191
	ds_read_b128 v[4:7], v8
	ds_read_b128 v[8:11], v8 offset:8192
	v_mfma_f32_32x32x16_bf16 v[162:177], v[12:15], v[214:217], v[162:177]
	v_mfma_f32_32x32x16_bf16 v[146:161], v[178:181], v[214:217], v[146:161]
	v_add_u32_e32 v12, 0x80, v17
	v_xad_u32 v178, v12, v190, v191
	ds_read_b128 v[12:15], v178
	ds_read_b128 v[178:181], v178 offset:8192
	v_mfma_f32_32x32x16_bf16 v[162:177], v[182:185], v[218:221], v[162:177]
	v_mfma_f32_32x32x16_bf16 v[146:161], v[186:189], v[218:221], v[146:161]
	v_add_u32_e32 v182, 0xa0, v17
	v_xad_u32 v186, v182, v190, v191
	ds_read_b128 v[182:185], v186
	ds_read_b128 v[186:189], v186 offset:8192
	s_waitcnt lgkmcnt(0)
	v_mfma_f32_32x32x16_bf16 v[162:177], v[4:7], v[222:225], v[162:177]
	v_mfma_f32_32x32x16_bf16 v[146:161], v[8:11], v[222:225], v[146:161]
	v_add_u32_e32 v4, 0xc0, v17
	v_xad_u32 v8, v4, v190, v191
	ds_read_b128 v[4:7], v8
	ds_read_b128 v[8:11], v8 offset:8192
	v_mfma_f32_32x32x16_bf16 v[162:177], v[12:15], v[226:229], v[162:177]
	v_mfma_f32_32x32x16_bf16 v[146:161], v[178:181], v[226:229], v[146:161]
	v_add_u32_e32 v12, 0xe0, v17
	v_xad_u32 v17, v12, v190, v191
	ds_read_b128 v[12:15], v17
	ds_read_b128 v[178:181], v17 offset:8192
	v_mfma_f32_32x32x16_bf16 v[162:177], v[182:185], v[230:233], v[162:177]
	v_mfma_f32_32x32x16_bf16 v[146:161], v[186:189], v[230:233], v[146:161]
	s_waitcnt lgkmcnt(0)
	v_mfma_f32_32x32x16_bf16 v[162:177], v[4:7], v[234:237], v[162:177]
	v_mfma_f32_32x32x16_bf16 v[146:161], v[8:11], v[234:237], v[146:161]
	v_mfma_f32_32x32x16_bf16 v[162:177], v[12:15], v[238:241], v[162:177]
	v_mfma_f32_32x32x16_bf16 v[146:161], v[178:181], v[238:241], v[146:161]
	s_add_i32 s23, s18, s20
	s_add_i32 s10, s20, 63
	s_add_i32 s8, s23, 0xffffe0bf
	s_cmpk_lt_i32 s8, 0xffa6
	s_cselect_b64 s[8:9], -1, 0
	s_cmp_lt_i32 s10, s15
	s_cselect_b64 s[12:13], -1, 0
	s_and_b64 s[10:11], s[12:13], s[8:9]
	s_mov_b64 s[8:9], -1
	s_and_b64 vcc, exec, s[10:11]
	v_lshlrev_b32_e32 v11, 2, v16
	s_cbranch_vccnz .LBB0_2768
	v_sub_u32_e32 v2, v11, v2
	v_add_u32_e32 v2, s23, v2
	s_add_i32 s23, 0, 0x18600
	v_lshl_add_u32 v2, v2, 2, s23
	ds_read2_b32 v[178:179], v2 offset0:0 offset1:1
	ds_read2_b32 v[180:181], v2 offset0:2 offset1:3
	ds_read2_b32 v[182:183], v2 offset0:8 offset1:9
	ds_read2_b32 v[184:185], v2 offset0:10 offset1:11
	ds_read2_b32 v[186:187], v2 offset0:16 offset1:17
	ds_read2_b32 v[188:189], v2 offset0:18 offset1:19
	ds_read2_b32 v[190:191], v2 offset0:24 offset1:25
	ds_read2_b32 v[192:193], v2 offset0:26 offset1:27
	ds_read2_b32 v[194:195], v2 offset0:32 offset1:33
	ds_read2_b32 v[196:197], v2 offset0:34 offset1:35
	ds_read2_b32 v[198:199], v2 offset0:40 offset1:41
	ds_read2_b32 v[200:201], v2 offset0:42 offset1:43
	ds_read2_b32 v[202:203], v2 offset0:48 offset1:49
	ds_read2_b32 v[204:205], v2 offset0:50 offset1:51
	ds_read2_b32 v[206:207], v2 offset0:56 offset1:57
	ds_read2_b32 v[208:209], v2 offset0:58 offset1:59
	s_waitcnt lgkmcnt(0)
	v_fmamk_f32 v162, v162, 0x3e0293ee, v178
	v_fmamk_f32 v146, v146, 0x3e0293ee, v194
	v_fmamk_f32 v163, v163, 0x3e0293ee, v179
	v_fmamk_f32 v147, v147, 0x3e0293ee, v195
	v_max_f32_e32 v2, v162, v146
	v_fmamk_f32 v164, v164, 0x3e0293ee, v180
	v_fmamk_f32 v148, v148, 0x3e0293ee, v196
	v_max3_f32 v2, v2, v163, v147
	v_fmamk_f32 v165, v165, 0x3e0293ee, v181
	v_fmamk_f32 v149, v149, 0x3e0293ee, v197
	v_max3_f32 v2, v2, v164, v148
	v_fmamk_f32 v166, v166, 0x3e0293ee, v182
	v_fmamk_f32 v150, v150, 0x3e0293ee, v198
	v_max3_f32 v2, v2, v165, v149
	v_fmamk_f32 v167, v167, 0x3e0293ee, v183
	v_fmamk_f32 v151, v151, 0x3e0293ee, v199
	v_max3_f32 v2, v2, v166, v150
	v_fmamk_f32 v168, v168, 0x3e0293ee, v184
	v_fmamk_f32 v152, v152, 0x3e0293ee, v200
	v_max3_f32 v2, v2, v167, v151
	v_fmamk_f32 v169, v169, 0x3e0293ee, v185
	v_fmamk_f32 v153, v153, 0x3e0293ee, v201
	v_max3_f32 v2, v2, v168, v152
	v_fmamk_f32 v170, v170, 0x3e0293ee, v186
	v_fmamk_f32 v154, v154, 0x3e0293ee, v202
	v_max3_f32 v2, v2, v169, v153
	v_fmamk_f32 v171, v171, 0x3e0293ee, v187
	v_fmamk_f32 v155, v155, 0x3e0293ee, v203
	v_max3_f32 v2, v2, v170, v154
	v_fmamk_f32 v172, v172, 0x3e0293ee, v188
	v_fmamk_f32 v156, v156, 0x3e0293ee, v204
	v_max3_f32 v2, v2, v171, v155
	v_fmamk_f32 v173, v173, 0x3e0293ee, v189
	v_fmamk_f32 v157, v157, 0x3e0293ee, v205
	v_max3_f32 v2, v2, v172, v156
	v_fmamk_f32 v174, v174, 0x3e0293ee, v190
	v_fmamk_f32 v158, v158, 0x3e0293ee, v206
	v_max3_f32 v2, v2, v173, v157
	v_fmamk_f32 v175, v175, 0x3e0293ee, v191
	v_fmamk_f32 v159, v159, 0x3e0293ee, v207
	v_max3_f32 v2, v2, v174, v158
	v_fmamk_f32 v176, v176, 0x3e0293ee, v192
	v_fmamk_f32 v160, v160, 0x3e0293ee, v208
	v_max3_f32 v2, v2, v175, v159
	v_fmamk_f32 v177, v177, 0x3e0293ee, v193
	v_fmamk_f32 v161, v161, 0x3e0293ee, v209
	v_max3_f32 v2, v2, v176, v160
	v_max3_f32 v4, v2, v177, v161
	s_mov_b64 s[8:9], 0
.LBB0_2768:
	s_andn2_b64 vcc, exec, s[8:9]
	v_mov_b32_e32 v2, 0
	s_cbranch_vccnz .LBB0_2770
	v_max_f32_e32 v4, v162, v146
	v_max3_f32 v4, v4, v163, v147
	v_max3_f32 v4, v4, v164, v148
	v_max3_f32 v4, v4, v165, v149
	v_max3_f32 v4, v4, v166, v150
	v_max3_f32 v4, v4, v167, v151
	v_max3_f32 v4, v4, v168, v152
	v_max3_f32 v4, v4, v169, v153
	v_max3_f32 v4, v4, v170, v154
	v_max3_f32 v4, v4, v171, v155
	v_max3_f32 v4, v4, v172, v156
	v_max3_f32 v4, v4, v173, v157
	v_max3_f32 v4, v4, v174, v158
	v_max3_f32 v4, v4, v175, v159
	v_max3_f32 v4, v4, v176, v160
	v_max3_f32 v4, v4, v177, v161
	v_fmamk_f32 v4, v4, 0x3e0293ee, v253

.LBB0_2777:
	v_lshl_add_u32 v8, v242, 5, s32
	ds_read_b128 v[12:15], v8 offset:16
	ds_read_b128 v[8:11], v8
	v_sub_f32_e32 v4, v253, v251
	v_fmamk_f32 v2, v162, 0x3e0293ee, v4
	v_exp_f32_e32 v194, v2
	v_fmamk_f32 v2, v146, 0x3e0293ee, v4
	v_exp_f32_e32 v178, v2
	v_fmamk_f32 v2, v163, 0x3e0293ee, v4
	v_exp_f32_e32 v195, v2
	v_fmamk_f32 v2, v147, 0x3e0293ee, v4
	v_exp_f32_e32 v179, v2
	v_fmamk_f32 v2, v164, 0x3e0293ee, v4
	v_exp_f32_e32 v196, v2
	v_fmamk_f32 v2, v148, 0x3e0293ee, v4
	v_exp_f32_e32 v180, v2
	v_fmamk_f32 v2, v165, 0x3e0293ee, v4
	v_exp_f32_e32 v197, v2
	v_fmamk_f32 v2, v149, 0x3e0293ee, v4
	v_exp_f32_e32 v181, v2
	v_pk_add_f32 v[6:7], v[194:195], v[178:179]
	v_fmamk_f32 v2, v166, 0x3e0293ee, v4
	v_exp_f32_e32 v198, v2
	v_fmamk_f32 v2, v150, 0x3e0293ee, v4
	v_exp_f32_e32 v182, v2
	v_fmamk_f32 v2, v167, 0x3e0293ee, v4
	v_exp_f32_e32 v199, v2
	v_fmamk_f32 v2, v151, 0x3e0293ee, v4
	v_exp_f32_e32 v183, v2
	v_pk_add_f32 v[6:7], v[6:7], v[196:197]
	v_pk_add_f32 v[6:7], v[6:7], v[180:181]
	v_fmamk_f32 v2, v168, 0x3e0293ee, v4
	v_exp_f32_e32 v200, v2
	v_fmamk_f32 v2, v152, 0x3e0293ee, v4
	v_exp_f32_e32 v184, v2
	v_fmamk_f32 v2, v169, 0x3e0293ee, v4
	v_exp_f32_e32 v201, v2
	v_fmamk_f32 v2, v153, 0x3e0293ee, v4
	v_exp_f32_e32 v185, v2
	v_pk_add_f32 v[6:7], v[6:7], v[198:199]
	v_pk_add_f32 v[6:7], v[6:7], v[182:183]
	v_fmamk_f32 v2, v170, 0x3e0293ee, v4
	v_exp_f32_e32 v202, v2
	v_fmamk_f32 v2, v154, 0x3e0293ee, v4
	v_exp_f32_e32 v186, v2
	v_fmamk_f32 v2, v171, 0x3e0293ee, v4
	v_exp_f32_e32 v203, v2
	v_fmamk_f32 v2, v155, 0x3e0293ee, v4
	v_exp_f32_e32 v187, v2
	v_pk_add_f32 v[6:7], v[6:7], v[200:201]
	v_pk_add_f32 v[6:7], v[6:7], v[184:185]
	v_fmamk_f32 v2, v172, 0x3e0293ee, v4
	v_exp_f32_e32 v204, v2
	v_fmamk_f32 v2, v156, 0x3e0293ee, v4
	v_exp_f32_e32 v188, v2
	v_fmamk_f32 v2, v173, 0x3e0293ee, v4
	v_exp_f32_e32 v205, v2
	v_fmamk_f32 v2, v157, 0x3e0293ee, v4
	v_exp_f32_e32 v189, v2
	v_pk_add_f32 v[6:7], v[6:7], v[202:203]
	v_pk_add_f32 v[6:7], v[6:7], v[186:187]
	v_fmamk_f32 v2, v174, 0x3e0293ee, v4
	v_exp_f32_e32 v206, v2
	v_fmamk_f32 v2, v158, 0x3e0293ee, v4
	v_exp_f32_e32 v190, v2
	v_fmamk_f32 v2, v175, 0x3e0293ee, v4
	v_exp_f32_e32 v207, v2
	v_fmamk_f32 v2, v159, 0x3e0293ee, v4
	v_exp_f32_e32 v191, v2
	v_pk_add_f32 v[6:7], v[6:7], v[204:205]
	v_pk_add_f32 v[6:7], v[6:7], v[188:189]
	v_fmamk_f32 v2, v176, 0x3e0293ee, v4
	v_exp_f32_e32 v208, v2
	v_fmamk_f32 v2, v160, 0x3e0293ee, v4
	v_exp_f32_e32 v192, v2
	v_fmamk_f32 v2, v177, 0x3e0293ee, v4
	v_exp_f32_e32 v209, v2
	v_pk_add_f32 v[6:7], v[6:7], v[206:207]
	v_pk_add_f32 v[6:7], v[6:7], v[190:191]
	v_fmac_f32_e32 v4, 0x3e0293ee, v161
	v_add_f32_e32 v7, v6, v7
	v_add_f32_e32 v7, v7, v208
	v_add_f32_e32 v7, v7, v192
	s_add_i32 s19, s19, 1
	s_cmp_ge_i32 s19, s16
	s_cbranch_scc1 .LBB0_2759
